# scan: per-lane address constants hoisted out of the chunk loop; second PREP pass no longer waits for the y-flush store (vmcnt(1))
# speedup vs baseline: 1.0053x; 1.0053x over previous
.Lmy_ck_nz:
	s_mov_b32 s100, 0xe000
	s_cmp_eq_u32 s23, 0
	s_cselect_b32 s100, 0x1c000, s100
	s_mov_b32 s101, 0x12e00
	s_cselect_b32 s101, 0x22100, s101
	s_lshl_b32 s96, s23, 13
	s_add_i32 s97, s96, 0x18000
	s_add_i32 s96, s96, 0xa000
	v_add_u32_e32 v225, s100, v1
	v_add_u32_e32 v236, s100, v0
	v_add_u32_e32 v226, s100, v2
	v_add_u32_e32 v227, s100, v3
	v_add_u32_e32 v228, s100, v4
	v_add_u32_e32 v229, s100, v5
	v_add_u32_e32 v237, s100, v6
	v_add_u32_e32 v238, s100, v7
	v_add_u32_e32 v230, s96, v8
	v_add_u32_e32 v239, s96, v9
	v_add_u32_e32 v231, s97, v8
	v_add_u32_e32 v26, s101, v1
	v_add_u32_e32 v27, s101, v0
	v_add_u32_e32 v28, s101, v2
	v_add_u32_e32 v29, s101, v3
	v_add_u32_e32 v30, s101, v4
	v_add_u32_e32 v31, s101, v5
	v_add_u32_e32 v32, s101, v6
	v_add_u32_e32 v33, s101, v7
	ds_read_b64 v[80:81], v237
	ds_read_b64 v[82:83], v238
	ds_read_b32 v84, v230
	ds_read_b32 v85, v230 offset:256
	ds_read_b32 v86, v230 offset:512
	ds_read_b32 v87, v230 offset:768
	ds_read_b32 v36, v239
	ds_read_b32 v37, v239 offset:256
	ds_read_b128 v[88:91], v225
	ds_read_b128 v[92:95], v225 offset:1024
	ds_read_b128 v[96:99], v225 offset:2048
	ds_read_b128 v[100:103], v225 offset:3072
	ds_read_b32 v104, v227 offset:4
	ds_read_b32 v105, v227 offset:76
	ds_read_b64 v[106:107], v227 offset:8
	ds_read_b64 v[108:109], v227 offset:40
	ds_read_b32 v126, v229 offset:4
	ds_read_b32 v127, v229 offset:76
	ds_read_b64 v[128:129], v229 offset:8
	ds_read_b64 v[130:131], v229 offset:40
	ds_read_b64 v[110:111], v228
	ds_read_b64 v[112:113], v228 offset:32
	ds_read_b64 v[114:115], v228 offset:64
	ds_read_b64 v[116:117], v228 offset:96
	ds_read_b64 v[118:119], v228 offset:8
	ds_read_b64 v[120:121], v228 offset:40
	ds_read_b64 v[122:123], v228 offset:72
	ds_read_b64 v[124:125], v228 offset:104
	s_waitcnt lgkmcnt(15)
	v_mfma_f32_16x16x4_f32 v[240:243], v80, v36, 0
	v_mfma_f32_16x16x4_f32 v[240:243], v81, v37, v[240:243]
	v_mfma_f32_16x16x4_f32 v[240:243], v88, v208, v[240:243]
	ds_read_b128 v[184:187], v236 offset:4096
	ds_read_b128 v[188:191], v236 offset:5120
	v_mfma_f32_16x16x4_f32 v[244:247], v89, v209, 0
	ds_read_b128 v[192:195], v236 offset:6144
	ds_read_b128 v[196:199], v236 offset:7168
	v_mfma_f32_16x16x4_f32 v[240:243], v90, v210, v[240:243]
	ds_read_b64 v[132:133], v237 offset:9984
	ds_read_b64 v[134:135], v238 offset:9984
	v_mfma_f32_16x16x4_f32 v[244:247], v91, v211, v[244:247]
	ds_read_b32 v136, v230 offset:2048
	ds_read_b32 v137, v230 offset:2304
	v_mfma_f32_16x16x4_f32 v[240:243], v92, v212, v[240:243]
	ds_read_b32 v138, v230 offset:2560
	ds_read_b32 v139, v230 offset:2816
	v_mfma_f32_16x16x4_f32 v[244:247], v93, v213, v[244:247]
	ds_read_b32 v38, v239 offset:2048
	ds_read_b32 v39, v239 offset:2304
	v_mfma_f32_16x16x4_f32 v[240:243], v94, v214, v[240:243]
	ds_read_b128 v[140:143], v225 offset:9984
	ds_read_b128 v[144:147], v225 offset:11008
	v_mfma_f32_16x16x4_f32 v[244:247], v95, v215, v[244:247]
	ds_read_b128 v[148:151], v225 offset:12032
	ds_read_b128 v[152:155], v225 offset:13056
	v_mfma_f32_16x16x4_f32 v[240:243], v96, v216, v[240:243]
	ds_read_b32 v156, v227 offset:9988
	ds_read_b32 v157, v227 offset:10060
	v_mfma_f32_16x16x4_f32 v[244:247], v97, v217, v[244:247]
	ds_read_b64 v[158:159], v227 offset:9992
	ds_read_b64 v[160:161], v227 offset:10024
	v_mfma_f32_16x16x4_f32 v[240:243], v98, v218, v[240:243]
	ds_read_b32 v178, v229 offset:9988
	ds_read_b32 v179, v229 offset:10060
	v_mfma_f32_16x16x4_f32 v[244:247], v99, v219, v[244:247]
	ds_read_b64 v[180:181], v229 offset:9992
	ds_read_b64 v[182:183], v229 offset:10024
	v_mfma_f32_16x16x4_f32 v[240:243], v100, v220, v[240:243]
	ds_read_b64 v[162:163], v228 offset:9984
	ds_read_b64 v[164:165], v228 offset:10016
	v_mfma_f32_16x16x4_f32 v[244:247], v101, v221, v[244:247]
	ds_read_b64 v[166:167], v228 offset:10048
	ds_read_b64 v[168:169], v228 offset:10080
	v_mfma_f32_16x16x4_f32 v[240:243], v102, v222, v[240:243]
	ds_read_b64 v[170:171], v228 offset:9992
	ds_read_b64 v[172:173], v228 offset:10024
	v_mfma_f32_16x16x4_f32 v[244:247], v103, v223, v[244:247]
	ds_read_b64 v[174:175], v228 offset:10056
	ds_read_b64 v[176:177], v228 offset:10088
	s_nop 7
	v_pk_add_f32 v[240:241], v[240:241], v[244:245]
	v_pk_add_f32 v[242:243], v[242:243], v[246:247]
	v_fmac_f32_e32 v241, v104, v240
	s_waitcnt lgkmcnt(13)
	v_pk_fma_f32 v[242:243], v[106:107], v[240:241], v[242:243] op_sel:[0,0,0] op_sel_hi:[1,0,1]
	v_pk_fma_f32 v[242:243], v[108:109], v[240:241], v[242:243] op_sel:[0,1,0] op_sel_hi:[1,1,1]
	v_fmac_f32_e32 v243, v105, v242
	ds_bpermute_b32 v204, v232, v240
	ds_bpermute_b32 v205, v232, v241
	ds_bpermute_b32 v206, v232, v242
	ds_bpermute_b32 v207, v232, v243
	ds_read_b128 v[88:91], v226
	ds_read_b128 v[92:95], v226 offset:64
	ds_read_b128 v[96:99], v226 offset:128
	ds_read_b128 v[100:103], v226 offset:192
	v_mfma_f32_16x16x4_f32 v[72:75], v132, v38, 0
	v_mfma_f32_16x16x4_f32 v[72:75], v133, v39, v[72:75]
	s_waitcnt lgkmcnt(6)
	v_pk_fma_f32 v[240:241], v[110:111], v[204:205], v[240:241] op_sel:[0,0,0] op_sel_hi:[1,0,1]
	v_pk_fma_f32 v[240:241], v[112:113], v[204:205], v[240:241] op_sel:[0,1,0] op_sel_hi:[1,1,1]
	s_waitcnt lgkmcnt(4)
	v_pk_fma_f32 v[240:241], v[114:115], v[206:207], v[240:241] op_sel:[0,0,0] op_sel_hi:[1,0,1]
	v_pk_fma_f32 v[240:241], v[116:117], v[206:207], v[240:241] op_sel:[0,1,0] op_sel_hi:[1,1,1]
	v_pk_fma_f32 v[242:243], v[118:119], v[204:205], v[242:243] op_sel:[0,0,0] op_sel_hi:[1,0,1]
	v_pk_fma_f32 v[242:243], v[120:121], v[204:205], v[242:243] op_sel:[0,1,0] op_sel_hi:[1,1,1]
	v_pk_fma_f32 v[242:243], v[122:123], v[206:207], v[242:243] op_sel:[0,0,0] op_sel_hi:[1,0,1]
	v_pk_fma_f32 v[242:243], v[124:125], v[206:207], v[242:243] op_sel:[0,1,0] op_sel_hi:[1,1,1]
	v_fmac_f32_e32 v241, v126, v240
	v_pk_fma_f32 v[242:243], v[128:129], v[240:241], v[242:243] op_sel:[0,0,0] op_sel_hi:[1,0,1]
	v_pk_fma_f32 v[242:243], v[130:131], v[240:241], v[242:243] op_sel:[0,1,0] op_sel_hi:[1,1,1]
	v_fmac_f32_e32 v243, v127, v242
	v_cndmask_b32_e64 v200, v240, v84, s[98:99]
	v_cndmask_b32_e64 v201, v241, v85, s[98:99]
	v_cndmask_b32_e64 v202, v242, v86, s[98:99]
	v_cndmask_b32_e64 v203, v243, v87, s[98:99]
	v_mov_b32_e32 v252, v240
	v_mov_b32_e32 v253, v241
	v_mov_b32_e32 v254, v242
	v_mov_b32_e32 v255, v243
	v_mfma_f32_16x16x4_f32 v[208:211], v184, v200, v[208:211]
	v_mfma_f32_16x16x4_f32 v[212:215], v188, v200, v[212:215]
	v_mfma_f32_16x16x4_f32 v[216:219], v192, v200, v[216:219]
	v_mfma_f32_16x16x4_f32 v[220:223], v196, v200, v[220:223]
	v_permlane32_swap_b32_e32 v252, v254
	v_permlane32_swap_b32_e32 v253, v255
	v_mfma_f32_16x16x4_f32 v[208:211], v185, v201, v[208:211]
	v_mfma_f32_16x16x4_f32 v[212:215], v189, v201, v[212:215]
	v_mfma_f32_16x16x4_f32 v[216:219], v193, v201, v[216:219]
	v_mfma_f32_16x16x4_f32 v[220:223], v197, v201, v[220:223]
	v_mfma_f32_16x16x4_f32 v[208:211], v186, v202, v[208:211]
	v_mfma_f32_16x16x4_f32 v[212:215], v190, v202, v[212:215]
	v_mfma_f32_16x16x4_f32 v[216:219], v194, v202, v[216:219]
	v_mfma_f32_16x16x4_f32 v[220:223], v198, v202, v[220:223]
	v_mfma_f32_16x16x4_f32 v[208:211], v187, v203, v[208:211]
	v_mfma_f32_16x16x4_f32 v[212:215], v191, v203, v[212:215]
	v_mfma_f32_16x16x4_f32 v[216:219], v195, v203, v[216:219]
	v_mfma_f32_16x16x4_f32 v[220:223], v199, v203, v[220:223]
	v_mfma_f32_16x16x4_f32 v[248:251], v82, v252, v[240:243]
	v_mfma_f32_16x16x4_f32 v[248:251], v83, v253, v[248:251]
	s_waitcnt lgkmcnt(0)
	s_nop 4
	v_pk_mul_f32 v[208:209], v[208:209], v[88:89]
	v_pk_mul_f32 v[210:211], v[210:211], v[90:91]
	s_nop 0
	v_mfma_f32_16x16x4_f32 v[72:75], v140, v208, v[72:75]
	v_pk_mul_f32 v[212:213], v[212:213], v[92:93]
	v_mfma_f32_16x16x4_f32 v[244:247], v141, v209, 0
	v_pk_mul_f32 v[214:215], v[214:215], v[94:95]
	v_mfma_f32_16x16x4_f32 v[72:75], v142, v210, v[72:75]
	v_pk_mul_f32 v[216:217], v[216:217], v[96:97]
	v_mfma_f32_16x16x4_f32 v[244:247], v143, v211, v[244:247]
	v_pk_mul_f32 v[218:219], v[218:219], v[98:99]
	v_mfma_f32_16x16x4_f32 v[72:75], v144, v212, v[72:75]
	v_pk_mul_f32 v[220:221], v[220:221], v[100:101]
	v_mfma_f32_16x16x4_f32 v[244:247], v145, v213, v[244:247]
	v_pk_mul_f32 v[222:223], v[222:223], v[102:103]
	v_mfma_f32_16x16x4_f32 v[72:75], v146, v214, v[72:75]
	s_mov_b64 exec, s[98:99]
	ds_write_b32 v231, v248
	ds_write_b32 v231, v249 offset:256
	ds_write_b32 v231, v250 offset:512
	ds_write_b32 v231, v251 offset:768
	s_mov_b64 exec, -1
	ds_read_b128 v[184:187], v236 offset:14080
	ds_read_b128 v[188:191], v236 offset:15104
	v_mfma_f32_16x16x4_f32 v[244:247], v147, v215, v[244:247]
	ds_read_b128 v[192:195], v236 offset:16128
	ds_read_b128 v[196:199], v236 offset:17152
	v_mfma_f32_16x16x4_f32 v[72:75], v148, v216, v[72:75]
	ds_read_b64 v[80:81], v32
	ds_read_b64 v[82:83], v33
	ds_read_b32 v84, v230 offset:4096
	ds_read_b32 v85, v230 offset:4352
	v_mfma_f32_16x16x4_f32 v[244:247], v149, v217, v[244:247]
	ds_read_b32 v86, v230 offset:4608
	ds_read_b32 v87, v230 offset:4864
	ds_read_b32 v36, v239 offset:4096
	ds_read_b32 v37, v239 offset:4352
	v_mfma_f32_16x16x4_f32 v[72:75], v150, v218, v[72:75]
	ds_read_b128 v[88:91], v26
	ds_read_b128 v[92:95], v26 offset:1024
	ds_read_b128 v[96:99], v26 offset:2048
	ds_read_b128 v[100:103], v26 offset:3072
	v_mfma_f32_16x16x4_f32 v[244:247], v151, v219, v[244:247]
	ds_read_b32 v104, v29 offset:4
	ds_read_b32 v105, v29 offset:76
	ds_read_b64 v[106:107], v29 offset:8
	ds_read_b64 v[108:109], v29 offset:40
	v_mfma_f32_16x16x4_f32 v[72:75], v152, v220, v[72:75]
	ds_read_b32 v126, v31 offset:4
	ds_read_b32 v127, v31 offset:76
	ds_read_b64 v[128:129], v31 offset:8
	ds_read_b64 v[130:131], v31 offset:40
	v_mfma_f32_16x16x4_f32 v[244:247], v153, v221, v[244:247]
	ds_read_b64 v[110:111], v30
	ds_read_b64 v[112:113], v30 offset:32
	ds_read_b64 v[114:115], v30 offset:64
	ds_read_b64 v[116:117], v30 offset:96
	v_mfma_f32_16x16x4_f32 v[72:75], v154, v222, v[72:75]
	ds_read_b64 v[118:119], v30 offset:8
	ds_read_b64 v[120:121], v30 offset:40
	ds_read_b64 v[122:123], v30 offset:72
	ds_read_b64 v[124:125], v30 offset:104
	v_mfma_f32_16x16x4_f32 v[244:247], v155, v223, v[244:247]
	s_nop 9
	v_pk_add_f32 v[72:73], v[72:73], v[244:245]
	v_pk_add_f32 v[74:75], v[74:75], v[246:247]
	v_fmac_f32_e32 v73, v156, v72
	v_pk_fma_f32 v[74:75], v[158:159], v[72:73], v[74:75] op_sel:[0,0,0] op_sel_hi:[1,0,1]
	v_pk_fma_f32 v[74:75], v[160:161], v[72:73], v[74:75] op_sel:[0,1,0] op_sel_hi:[1,1,1]
	v_fmac_f32_e32 v75, v157, v74
	ds_bpermute_b32 v204, v232, v72
	ds_bpermute_b32 v205, v232, v73
	ds_bpermute_b32 v206, v232, v74
	ds_bpermute_b32 v207, v232, v75
	ds_read_b128 v[140:143], v226 offset:9984
	ds_read_b128 v[144:147], v226 offset:10048
	ds_read_b128 v[148:151], v226 offset:10112
	ds_read_b128 v[152:155], v226 offset:10176
	s_waitcnt lgkmcnt(14)
	v_mfma_f32_16x16x4_f32 v[240:243], v80, v36, 0
	v_mfma_f32_16x16x4_f32 v[240:243], v81, v37, v[240:243]
	s_waitcnt lgkmcnt(6)
	v_pk_fma_f32 v[72:73], v[162:163], v[204:205], v[72:73] op_sel:[0,0,0] op_sel_hi:[1,0,1]
	v_pk_fma_f32 v[72:73], v[164:165], v[204:205], v[72:73] op_sel:[0,1,0] op_sel_hi:[1,1,1]
	s_waitcnt lgkmcnt(4)
	v_pk_fma_f32 v[72:73], v[166:167], v[206:207], v[72:73] op_sel:[0,0,0] op_sel_hi:[1,0,1]
	v_pk_fma_f32 v[72:73], v[168:169], v[206:207], v[72:73] op_sel:[0,1,0] op_sel_hi:[1,1,1]
	v_pk_fma_f32 v[74:75], v[170:171], v[204:205], v[74:75] op_sel:[0,0,0] op_sel_hi:[1,0,1]
	v_pk_fma_f32 v[74:75], v[172:173], v[204:205], v[74:75] op_sel:[0,1,0] op_sel_hi:[1,1,1]
	v_pk_fma_f32 v[74:75], v[174:175], v[206:207], v[74:75] op_sel:[0,0,0] op_sel_hi:[1,0,1]
	v_pk_fma_f32 v[74:75], v[176:177], v[206:207], v[74:75] op_sel:[0,1,0] op_sel_hi:[1,1,1]
	v_fmac_f32_e32 v73, v178, v72
	v_pk_fma_f32 v[74:75], v[180:181], v[72:73], v[74:75] op_sel:[0,0,0] op_sel_hi:[1,0,1]
	v_pk_fma_f32 v[74:75], v[182:183], v[72:73], v[74:75] op_sel:[0,1,0] op_sel_hi:[1,1,1]
	v_fmac_f32_e32 v75, v179, v74
	v_cndmask_b32_e64 v200, v72, v136, s[98:99]
	v_cndmask_b32_e64 v201, v73, v137, s[98:99]
	v_cndmask_b32_e64 v202, v74, v138, s[98:99]
	v_cndmask_b32_e64 v203, v75, v139, s[98:99]
	v_mov_b32_e32 v252, v72
	v_mov_b32_e32 v253, v73
	v_mov_b32_e32 v254, v74
	v_mov_b32_e32 v255, v75
	v_mfma_f32_16x16x4_f32 v[208:211], v184, v200, v[208:211]
	v_mfma_f32_16x16x4_f32 v[212:215], v188, v200, v[212:215]
	v_mfma_f32_16x16x4_f32 v[216:219], v192, v200, v[216:219]
	v_mfma_f32_16x16x4_f32 v[220:223], v196, v200, v[220:223]
	v_permlane32_swap_b32_e32 v252, v254
	v_permlane32_swap_b32_e32 v253, v255
	v_mfma_f32_16x16x4_f32 v[208:211], v185, v201, v[208:211]
	v_mfma_f32_16x16x4_f32 v[212:215], v189, v201, v[212:215]
	v_mfma_f32_16x16x4_f32 v[216:219], v193, v201, v[216:219]
	v_mfma_f32_16x16x4_f32 v[220:223], v197, v201, v[220:223]
	v_mfma_f32_16x16x4_f32 v[208:211], v186, v202, v[208:211]
	v_mfma_f32_16x16x4_f32 v[212:215], v190, v202, v[212:215]
	v_mfma_f32_16x16x4_f32 v[216:219], v194, v202, v[216:219]
	v_mfma_f32_16x16x4_f32 v[220:223], v198, v202, v[220:223]
	v_mfma_f32_16x16x4_f32 v[208:211], v187, v203, v[208:211]
	v_mfma_f32_16x16x4_f32 v[212:215], v191, v203, v[212:215]
	v_mfma_f32_16x16x4_f32 v[216:219], v195, v203, v[216:219]
	v_mfma_f32_16x16x4_f32 v[220:223], v199, v203, v[220:223]
	v_mfma_f32_16x16x4_f32 v[248:251], v134, v252, v[72:75]
	v_mfma_f32_16x16x4_f32 v[248:251], v135, v253, v[248:251]
	s_waitcnt lgkmcnt(0)
	s_nop 4
	v_pk_mul_f32 v[208:209], v[208:209], v[140:141]
	v_pk_mul_f32 v[210:211], v[210:211], v[142:143]
	s_nop 0
	v_mfma_f32_16x16x4_f32 v[240:243], v88, v208, v[240:243]
	v_pk_mul_f32 v[212:213], v[212:213], v[144:145]
	v_mfma_f32_16x16x4_f32 v[244:247], v89, v209, 0
	v_pk_mul_f32 v[214:215], v[214:215], v[146:147]
	v_mfma_f32_16x16x4_f32 v[240:243], v90, v210, v[240:243]
	v_pk_mul_f32 v[216:217], v[216:217], v[148:149]
	v_mfma_f32_16x16x4_f32 v[244:247], v91, v211, v[244:247]
	v_pk_mul_f32 v[218:219], v[218:219], v[150:151]
	v_mfma_f32_16x16x4_f32 v[240:243], v92, v212, v[240:243]
	v_pk_mul_f32 v[220:221], v[220:221], v[152:153]
	v_mfma_f32_16x16x4_f32 v[244:247], v93, v213, v[244:247]
	v_pk_mul_f32 v[222:223], v[222:223], v[154:155]
	v_mfma_f32_16x16x4_f32 v[240:243], v94, v214, v[240:243]
	s_mov_b64 exec, s[98:99]
	ds_write_b32 v231, v248 offset:2048
	ds_write_b32 v231, v249 offset:2304
	ds_write_b32 v231, v250 offset:2560
	ds_write_b32 v231, v251 offset:2816
	s_mov_b64 exec, -1
	ds_read_b128 v[184:187], v27 offset:4096
	ds_read_b128 v[188:191], v27 offset:5120
	v_mfma_f32_16x16x4_f32 v[244:247], v95, v215, v[244:247]
	ds_read_b128 v[192:195], v27 offset:6144
	ds_read_b128 v[196:199], v27 offset:7168
	v_mfma_f32_16x16x4_f32 v[240:243], v96, v216, v[240:243]
	ds_read_b64 v[132:133], v32 offset:9984
	ds_read_b64 v[134:135], v33 offset:9984
	ds_read_b32 v136, v230 offset:6144
	ds_read_b32 v137, v230 offset:6400
	v_mfma_f32_16x16x4_f32 v[244:247], v97, v217, v[244:247]
	ds_read_b32 v138, v230 offset:6656
	ds_read_b32 v139, v230 offset:6912
	ds_read_b32 v38, v239 offset:6144
	ds_read_b32 v39, v239 offset:6400
	v_mfma_f32_16x16x4_f32 v[240:243], v98, v218, v[240:243]
	ds_read_b128 v[140:143], v26 offset:9984
	ds_read_b128 v[144:147], v26 offset:11008
	ds_read_b128 v[148:151], v26 offset:12032
	ds_read_b128 v[152:155], v26 offset:13056
	v_mfma_f32_16x16x4_f32 v[244:247], v99, v219, v[244:247]
	ds_read_b32 v156, v29 offset:9988
	ds_read_b32 v157, v29 offset:10060
	ds_read_b64 v[158:159], v29 offset:9992
	ds_read_b64 v[160:161], v29 offset:10024
	v_mfma_f32_16x16x4_f32 v[240:243], v100, v220, v[240:243]
	ds_read_b32 v178, v31 offset:9988
	ds_read_b32 v179, v31 offset:10060
	ds_read_b64 v[180:181], v31 offset:9992
	ds_read_b64 v[182:183], v31 offset:10024
	v_mfma_f32_16x16x4_f32 v[244:247], v101, v221, v[244:247]
	ds_read_b64 v[162:163], v30 offset:9984
	ds_read_b64 v[164:165], v30 offset:10016
	ds_read_b64 v[166:167], v30 offset:10048
	ds_read_b64 v[168:169], v30 offset:10080
	v_mfma_f32_16x16x4_f32 v[240:243], v102, v222, v[240:243]
	ds_read_b64 v[170:171], v30 offset:9992
	ds_read_b64 v[172:173], v30 offset:10024
	ds_read_b64 v[174:175], v30 offset:10056
	ds_read_b64 v[176:177], v30 offset:10088
	v_mfma_f32_16x16x4_f32 v[244:247], v103, v223, v[244:247]
	s_nop 9
	v_pk_add_f32 v[240:241], v[240:241], v[244:245]
	v_pk_add_f32 v[242:243], v[242:243], v[246:247]
	v_fmac_f32_e32 v241, v104, v240
	v_pk_fma_f32 v[242:243], v[106:107], v[240:241], v[242:243] op_sel:[0,0,0] op_sel_hi:[1,0,1]
	v_pk_fma_f32 v[242:243], v[108:109], v[240:241], v[242:243] op_sel:[0,1,0] op_sel_hi:[1,1,1]
	v_fmac_f32_e32 v243, v105, v242
	ds_bpermute_b32 v204, v232, v240
	ds_bpermute_b32 v205, v232, v241
	ds_bpermute_b32 v206, v232, v242
	ds_bpermute_b32 v207, v232, v243
	ds_read_b128 v[88:91], v28
	ds_read_b128 v[92:95], v28 offset:64
	ds_read_b128 v[96:99], v28 offset:128
	ds_read_b128 v[100:103], v28 offset:192
	s_waitcnt lgkmcnt(14)
	v_mfma_f32_16x16x4_f32 v[72:75], v132, v38, 0
	v_mfma_f32_16x16x4_f32 v[72:75], v133, v39, v[72:75]
	s_waitcnt lgkmcnt(6)
	v_pk_fma_f32 v[240:241], v[110:111], v[204:205], v[240:241] op_sel:[0,0,0] op_sel_hi:[1,0,1]
	v_pk_fma_f32 v[240:241], v[112:113], v[204:205], v[240:241] op_sel:[0,1,0] op_sel_hi:[1,1,1]
	s_waitcnt lgkmcnt(4)
	v_pk_fma_f32 v[240:241], v[114:115], v[206:207], v[240:241] op_sel:[0,0,0] op_sel_hi:[1,0,1]
	v_pk_fma_f32 v[240:241], v[116:117], v[206:207], v[240:241] op_sel:[0,1,0] op_sel_hi:[1,1,1]
	v_pk_fma_f32 v[242:243], v[118:119], v[204:205], v[242:243] op_sel:[0,0,0] op_sel_hi:[1,0,1]
	v_pk_fma_f32 v[242:243], v[120:121], v[204:205], v[242:243] op_sel:[0,1,0] op_sel_hi:[1,1,1]
	v_pk_fma_f32 v[242:243], v[122:123], v[206:207], v[242:243] op_sel:[0,0,0] op_sel_hi:[1,0,1]
	v_pk_fma_f32 v[242:243], v[124:125], v[206:207], v[242:243] op_sel:[0,1,0] op_sel_hi:[1,1,1]
	v_fmac_f32_e32 v241, v126, v240
	v_pk_fma_f32 v[242:243], v[128:129], v[240:241], v[242:243] op_sel:[0,0,0] op_sel_hi:[1,0,1]
	v_pk_fma_f32 v[242:243], v[130:131], v[240:241], v[242:243] op_sel:[0,1,0] op_sel_hi:[1,1,1]
	v_fmac_f32_e32 v243, v127, v242
	v_cndmask_b32_e64 v200, v240, v84, s[98:99]
	v_cndmask_b32_e64 v201, v241, v85, s[98:99]
	v_cndmask_b32_e64 v202, v242, v86, s[98:99]
	v_cndmask_b32_e64 v203, v243, v87, s[98:99]
	v_mov_b32_e32 v252, v240
	v_mov_b32_e32 v253, v241
	v_mov_b32_e32 v254, v242
	v_mov_b32_e32 v255, v243
	v_mfma_f32_16x16x4_f32 v[208:211], v184, v200, v[208:211]
	v_mfma_f32_16x16x4_f32 v[212:215], v188, v200, v[212:215]
	v_mfma_f32_16x16x4_f32 v[216:219], v192, v200, v[216:219]
	v_mfma_f32_16x16x4_f32 v[220:223], v196, v200, v[220:223]
	v_permlane32_swap_b32_e32 v252, v254
	v_permlane32_swap_b32_e32 v253, v255
	v_mfma_f32_16x16x4_f32 v[208:211], v185, v201, v[208:211]
	v_mfma_f32_16x16x4_f32 v[212:215], v189, v201, v[212:215]
	v_mfma_f32_16x16x4_f32 v[216:219], v193, v201, v[216:219]
	v_mfma_f32_16x16x4_f32 v[220:223], v197, v201, v[220:223]
	v_mfma_f32_16x16x4_f32 v[208:211], v186, v202, v[208:211]
	v_mfma_f32_16x16x4_f32 v[212:215], v190, v202, v[212:215]
	v_mfma_f32_16x16x4_f32 v[216:219], v194, v202, v[216:219]
	v_mfma_f32_16x16x4_f32 v[220:223], v198, v202, v[220:223]
	v_mfma_f32_16x16x4_f32 v[208:211], v187, v203, v[208:211]
	v_mfma_f32_16x16x4_f32 v[212:215], v191, v203, v[212:215]
	v_mfma_f32_16x16x4_f32 v[216:219], v195, v203, v[216:219]
	v_mfma_f32_16x16x4_f32 v[220:223], v199, v203, v[220:223]
	v_mfma_f32_16x16x4_f32 v[248:251], v82, v252, v[240:243]
	v_mfma_f32_16x16x4_f32 v[248:251], v83, v253, v[248:251]
	s_waitcnt lgkmcnt(0)
	s_nop 4
	v_pk_mul_f32 v[208:209], v[208:209], v[88:89]
	v_pk_mul_f32 v[210:211], v[210:211], v[90:91]
	s_nop 0
	v_mfma_f32_16x16x4_f32 v[72:75], v140, v208, v[72:75]
	v_pk_mul_f32 v[212:213], v[212:213], v[92:93]
	v_mfma_f32_16x16x4_f32 v[244:247], v141, v209, 0
	v_pk_mul_f32 v[214:215], v[214:215], v[94:95]
	v_mfma_f32_16x16x4_f32 v[72:75], v142, v210, v[72:75]
	v_pk_mul_f32 v[216:217], v[216:217], v[96:97]
	v_mfma_f32_16x16x4_f32 v[244:247], v143, v211, v[244:247]
	v_pk_mul_f32 v[218:219], v[218:219], v[98:99]
	v_mfma_f32_16x16x4_f32 v[72:75], v144, v212, v[72:75]
	v_pk_mul_f32 v[220:221], v[220:221], v[100:101]
	v_mfma_f32_16x16x4_f32 v[244:247], v145, v213, v[244:247]
	v_pk_mul_f32 v[222:223], v[222:223], v[102:103]
	v_mfma_f32_16x16x4_f32 v[72:75], v146, v214, v[72:75]
	s_mov_b64 exec, s[98:99]
	ds_write_b32 v231, v248 offset:4096
	ds_write_b32 v231, v249 offset:4352
	ds_write_b32 v231, v250 offset:4608
	ds_write_b32 v231, v251 offset:4864
	s_mov_b64 exec, -1
	ds_read_b128 v[184:187], v27 offset:14080
	ds_read_b128 v[188:191], v27 offset:15104
	v_mfma_f32_16x16x4_f32 v[244:247], v147, v215, v[244:247]
	ds_read_b128 v[192:195], v27 offset:16128
	ds_read_b128 v[196:199], v27 offset:17152
	v_mfma_f32_16x16x4_f32 v[72:75], v148, v216, v[72:75]
	v_mfma_f32_16x16x4_f32 v[244:247], v149, v217, v[244:247]
	v_mfma_f32_16x16x4_f32 v[72:75], v150, v218, v[72:75]
	v_mfma_f32_16x16x4_f32 v[244:247], v151, v219, v[244:247]
	v_mfma_f32_16x16x4_f32 v[72:75], v152, v220, v[72:75]
	v_mfma_f32_16x16x4_f32 v[244:247], v153, v221, v[244:247]
	v_mfma_f32_16x16x4_f32 v[72:75], v154, v222, v[72:75]
	v_mfma_f32_16x16x4_f32 v[244:247], v155, v223, v[244:247]
	s_nop 9
	v_pk_add_f32 v[72:73], v[72:73], v[244:245]
	v_pk_add_f32 v[74:75], v[74:75], v[246:247]
	v_fmac_f32_e32 v73, v156, v72
	v_pk_fma_f32 v[74:75], v[158:159], v[72:73], v[74:75] op_sel:[0,0,0] op_sel_hi:[1,0,1]
	v_pk_fma_f32 v[74:75], v[160:161], v[72:73], v[74:75] op_sel:[0,1,0] op_sel_hi:[1,1,1]
	v_fmac_f32_e32 v75, v157, v74
	ds_bpermute_b32 v204, v232, v72
	ds_bpermute_b32 v205, v232, v73
	ds_bpermute_b32 v206, v232, v74
	ds_bpermute_b32 v207, v232, v75
	ds_read_b128 v[140:143], v28 offset:9984
	ds_read_b128 v[144:147], v28 offset:10048
	ds_read_b128 v[148:151], v28 offset:10112
	ds_read_b128 v[152:155], v28 offset:10176
	s_waitcnt lgkmcnt(6)
	v_pk_fma_f32 v[72:73], v[162:163], v[204:205], v[72:73] op_sel:[0,0,0] op_sel_hi:[1,0,1]
	v_pk_fma_f32 v[72:73], v[164:165], v[204:205], v[72:73] op_sel:[0,1,0] op_sel_hi:[1,1,1]
	s_waitcnt lgkmcnt(4)
	v_pk_fma_f32 v[72:73], v[166:167], v[206:207], v[72:73] op_sel:[0,0,0] op_sel_hi:[1,0,1]
	v_pk_fma_f32 v[72:73], v[168:169], v[206:207], v[72:73] op_sel:[0,1,0] op_sel_hi:[1,1,1]
	v_pk_fma_f32 v[74:75], v[170:171], v[204:205], v[74:75] op_sel:[0,0,0] op_sel_hi:[1,0,1]
	v_pk_fma_f32 v[74:75], v[172:173], v[204:205], v[74:75] op_sel:[0,1,0] op_sel_hi:[1,1,1]
	v_pk_fma_f32 v[74:75], v[174:175], v[206:207], v[74:75] op_sel:[0,0,0] op_sel_hi:[1,0,1]
	v_pk_fma_f32 v[74:75], v[176:177], v[206:207], v[74:75] op_sel:[0,1,0] op_sel_hi:[1,1,1]
	v_fmac_f32_e32 v73, v178, v72
	v_pk_fma_f32 v[74:75], v[180:181], v[72:73], v[74:75] op_sel:[0,0,0] op_sel_hi:[1,0,1]
	v_pk_fma_f32 v[74:75], v[182:183], v[72:73], v[74:75] op_sel:[0,1,0] op_sel_hi:[1,1,1]
	v_fmac_f32_e32 v75, v179, v74
	v_cndmask_b32_e64 v200, v72, v136, s[98:99]
	v_cndmask_b32_e64 v201, v73, v137, s[98:99]
	v_cndmask_b32_e64 v202, v74, v138, s[98:99]
	v_cndmask_b32_e64 v203, v75, v139, s[98:99]
	v_mov_b32_e32 v252, v72
	v_mov_b32_e32 v253, v73
	v_mov_b32_e32 v254, v74
	v_mov_b32_e32 v255, v75
	v_mfma_f32_16x16x4_f32 v[208:211], v184, v200, v[208:211]
	v_mfma_f32_16x16x4_f32 v[212:215], v188, v200, v[212:215]
	v_mfma_f32_16x16x4_f32 v[216:219], v192, v200, v[216:219]
	v_mfma_f32_16x16x4_f32 v[220:223], v196, v200, v[220:223]
	v_permlane32_swap_b32_e32 v252, v254
	v_permlane32_swap_b32_e32 v253, v255
	v_mfma_f32_16x16x4_f32 v[208:211], v185, v201, v[208:211]
	v_mfma_f32_16x16x4_f32 v[212:215], v189, v201, v[212:215]
	v_mfma_f32_16x16x4_f32 v[216:219], v193, v201, v[216:219]
	v_mfma_f32_16x16x4_f32 v[220:223], v197, v201, v[220:223]
	v_mfma_f32_16x16x4_f32 v[208:211], v186, v202, v[208:211]
	v_mfma_f32_16x16x4_f32 v[212:215], v190, v202, v[212:215]
	v_mfma_f32_16x16x4_f32 v[216:219], v194, v202, v[216:219]
	v_mfma_f32_16x16x4_f32 v[220:223], v198, v202, v[220:223]
	v_mfma_f32_16x16x4_f32 v[208:211], v187, v203, v[208:211]
	v_mfma_f32_16x16x4_f32 v[212:215], v191, v203, v[212:215]
	v_mfma_f32_16x16x4_f32 v[216:219], v195, v203, v[216:219]
	v_mfma_f32_16x16x4_f32 v[220:223], v199, v203, v[220:223]
	v_mfma_f32_16x16x4_f32 v[248:251], v134, v252, v[72:75]
	v_mfma_f32_16x16x4_f32 v[248:251], v135, v253, v[248:251]
	s_waitcnt lgkmcnt(0)
	s_nop 4
	v_pk_mul_f32 v[208:209], v[208:209], v[140:141]
	v_pk_mul_f32 v[210:211], v[210:211], v[142:143]
	v_pk_mul_f32 v[212:213], v[212:213], v[144:145]
	v_pk_mul_f32 v[214:215], v[214:215], v[146:147]
	v_pk_mul_f32 v[216:217], v[216:217], v[148:149]
	v_pk_mul_f32 v[218:219], v[218:219], v[150:151]
	v_pk_mul_f32 v[220:221], v[220:221], v[152:153]
	v_pk_mul_f32 v[222:223], v[222:223], v[154:155]
	s_mov_b64 exec, s[98:99]
	ds_write_b32 v231, v248 offset:6144
	ds_write_b32 v231, v249 offset:6400
	ds_write_b32 v231, v250 offset:6656
	ds_write_b32 v231, v251 offset:6912
	s_mov_b64 exec, -1
	s_branch .LBB0_655
.Lmy_f_hlp:
	s_cmp_eq_u32 s65, 63
	s_cbranch_scc0 .Lmy_f_hl2
	s_branch .LBB0_655

.Lmy_f_nol2:
	s_lshl_b32 s96, s101, 8
	v_add_u32_e32 v67, s96, v67
	s_andn2_b64 vcc, exec, s[50:51]
	s_cbranch_vccnz .LBB0_655
	s_waitcnt vmcnt(15)
	v_lshlrev_b32_e32 v72, 16, v28
	v_and_b32_e32 v73, 0xffff0000, v28
	v_lshlrev_b32_e32 v76, 16, v30
	v_and_b32_e32 v77, 0xffff0000, v30
	v_lshlrev_b32_e32 v74, 16, v26
	v_and_b32_e32 v75, 0xffff0000, v26
	v_pk_add_f32 v[72:73], v[72:73], v[76:77]
	s_waitcnt vmcnt(13)
	v_lshlrev_b32_e32 v78, 16, v42
	v_pk_fma_f32 v[72:73], v[72:73], 0.5, v[74:75] op_sel_hi:[1,0,1] neg_lo:[0,0,1] neg_hi:[0,0,1]
	v_and_b32_e32 v79, 0xffff0000, v42
	v_pk_fma_f32 v[72:73], v[0:1], v[72:73], v[74:75]
	v_lshlrev_b32_e32 v74, 16, v40
	v_and_b32_e32 v75, 0xffff0000, v40
	v_lshlrev_b32_e32 v76, 16, v38
	v_and_b32_e32 v77, 0xffff0000, v38
	v_pk_add_f32 v[74:75], v[74:75], v[78:79]
	s_waitcnt vmcnt(12)
	v_cvt_f32_f16_e32 v21, v44
	v_pk_fma_f32 v[74:75], v[74:75], 0.5, v[76:77] op_sel_hi:[1,0,1] neg_lo:[0,0,1] neg_hi:[0,0,1]
	v_lshlrev_b32_e32 v80, 16, v31
	v_pk_fma_f32 v[76:77], v[8:9], v[74:75], v[76:77]
	v_lshlrev_b32_e32 v74, 16, v29
	v_and_b32_e32 v75, 0xffff0000, v29
	v_and_b32_e32 v81, 0xffff0000, v31
	v_lshlrev_b32_e32 v78, 16, v27
	v_and_b32_e32 v79, 0xffff0000, v27
	v_pk_add_f32 v[74:75], v[74:75], v[80:81]
	v_cvt_f32_f16_sdwa v84, v44 dst_sel:DWORD dst_unused:UNUSED_PAD src0_sel:WORD_1
	v_pk_fma_f32 v[74:75], v[74:75], 0.5, v[78:79] op_sel_hi:[1,0,1] neg_lo:[0,0,1] neg_hi:[0,0,1]
	v_lshlrev_b32_e32 v82, 16, v43
	v_pk_fma_f32 v[74:75], v[2:3], v[74:75], v[78:79]
	v_lshlrev_b32_e32 v78, 16, v41
	v_and_b32_e32 v79, 0xffff0000, v41
	v_and_b32_e32 v83, 0xffff0000, v43
	v_cvt_f32_f16_e32 v88, v45
	v_lshlrev_b32_e32 v80, 16, v39
	v_and_b32_e32 v81, 0xffff0000, v39
	v_pk_add_f32 v[78:79], v[78:79], v[82:83]
	v_mul_f32_e32 v21, 0xbf1b4598, v21
	v_pk_fma_f32 v[78:79], v[78:79], 0.5, v[80:81] op_sel_hi:[1,0,1] neg_lo:[0,0,1] neg_hi:[0,0,1]
	v_mul_f32_e32 v21, 0x3fb8aa3b, v21
	v_cvt_f32_f16_sdwa v89, v45 dst_sel:DWORD dst_unused:UNUSED_PAD src0_sel:WORD_1
	v_pk_fma_f32 v[78:79], v[10:11], v[78:79], v[80:81]
	v_exp_f32_e32 v80, v21
	v_mul_f32_e32 v21, 0xbf1b4598, v84
	v_mul_f32_e32 v21, 0x3fb8aa3b, v21
	v_lshlrev_b32_e32 v82, 16, v34
	v_and_b32_e32 v83, 0xffff0000, v34
	v_lshlrev_b32_e32 v86, 16, v36
	v_and_b32_e32 v87, 0xffff0000, v36
	v_exp_f32_e32 v81, v21
	v_lshlrev_b32_e32 v84, 16, v32
	v_and_b32_e32 v85, 0xffff0000, v32
	v_pk_add_f32 v[82:83], v[82:83], v[86:87]
	v_mul_f32_e32 v21, 0xbf1b4598, v88
	v_pk_fma_f32 v[82:83], v[82:83], 0.5, v[84:85] op_sel_hi:[1,0,1] neg_lo:[0,0,1] neg_hi:[0,0,1]
	v_mul_f32_e32 v21, 0x3fb8aa3b, v21
	v_pk_fma_f32 v[96:97], v[4:5], v[82:83], v[84:85]
	v_exp_f32_e32 v82, v21
	v_mul_f32_e32 v21, 0xbf1b4598, v89
	v_lshlrev_b32_e32 v84, 16, v35
	v_and_b32_e32 v85, 0xffff0000, v35
	v_lshlrev_b32_e32 v88, 16, v37
	v_and_b32_e32 v89, 0xffff0000, v37
	v_lshlrev_b32_e32 v86, 16, v33
	v_and_b32_e32 v87, 0xffff0000, v33
	v_pk_add_f32 v[84:85], v[84:85], v[88:89]
	s_waitcnt vmcnt(11)
	v_cvt_f32_f16_sdwa v93, v46 dst_sel:DWORD dst_unused:UNUSED_PAD src0_sel:WORD_1
	v_pk_fma_f32 v[84:85], v[84:85], 0.5, v[86:87] op_sel_hi:[1,0,1] neg_lo:[0,0,1] neg_hi:[0,0,1]
	v_cvt_f32_f16_e32 v92, v46
	v_pk_fma_f32 v[94:95], v[6:7], v[84:85], v[86:87]
	v_pk_mul_f32 v[84:85], v[12:13], v[96:97]
	v_pk_mul_f32 v[88:89], v[14:15], v[94:95]
	v_pk_mul_f32 v[86:87], v[84:85], v[84:85]
	v_pk_mul_f32 v[90:91], v[88:89], v[88:89]
	v_add_f32_e32 v83, v86, v87
	v_add_f32_e32 v83, v90, v83
	v_add_f32_e32 v83, v91, v83
	v_cvt_f32_f16_sdwa v99, v47 dst_sel:DWORD dst_unused:UNUSED_PAD src0_sel:WORD_1
	v_cvt_f32_f16_e32 v98, v47
	v_add_f32_dpp v83, v83, v83 quad_perm:[1,0,3,2] row_mask:0xf bank_mask:0xf bound_ctrl:1
	v_mul_f32_e32 v21, 0x3fb8aa3b, v21
	s_bitcmp1_b32 s22, 0
	v_add_f32_dpp v83, v83, v83 quad_perm:[2,3,0,1] row_mask:0xf bank_mask:0xf bound_ctrl:1
	s_cselect_b32 s23, 0x2000, 0
	s_nop 0
	v_add_f32_dpp v83, v83, v83 row_half_mirror row_mask:0xf bank_mask:0xf bound_ctrl:1
	s_nop 1
	v_add_f32_dpp v83, v83, v83 row_mirror row_mask:0xf bank_mask:0xf bound_ctrl:1
	v_max_f32_e32 v83, 0x179abe15, v83
	v_rsq_f32_e32 v86, v83
	v_exp_f32_e32 v83, v21
	v_add_u32_e32 v21, s23, v67
	v_pk_mul_f32 v[90:91], v[84:85], v[86:87] op_sel_hi:[1,0]
	v_pk_mul_f32 v[100:101], v[88:89], v[86:87] op_sel_hi:[1,0]
	v_xor_b32_e32 v85, 0x80000000, v91
	v_xor_b32_e32 v84, 0x80000000, v90
	v_pk_mul_f32 v[88:89], v[90:91], v[92:93]
	v_pk_mul_f32 v[90:91], v[100:101], v[98:99]
	v_pk_add_f32 v[92:93], v[92:93], -1.0 op_sel_hi:[1,0]
	v_pk_add_f32 v[98:99], v[98:99], -1.0 op_sel_hi:[1,0]
	v_pk_fma_f32 v[92:93], v[16:17], v[92:93], 1.0 op_sel_hi:[1,1,0]
	v_pk_fma_f32 v[98:99], v[18:19], v[98:99], 1.0 op_sel_hi:[1,1,0]
	v_xor_b32_e32 v86, 0x80000000, v100
	v_xor_b32_e32 v87, 0x80000000, v101
	v_pk_mul_f32 v[94:95], v[94:95], v[98:99]
	v_pk_mul_f32 v[92:93], v[96:97], v[92:93]
	ds_write_b128 v67, v[80:83]
	ds_write_b128 v67, v[84:87] offset:8192
	ds_write_b128 v67, v[88:91] offset:16384
	ds_write_b128 v67, v[92:95] offset:24576
	ds_write_b128 v67, v[72:75] offset:32768
	ds_write_b128 v21, v[76:79] offset:40960
	v_add_u32_e32 v67, 0x400, v67
	s_cmp_lg_u32 s65, 0
	s_cbranch_scc1 .Lmy_f_p2w
	s_waitcnt vmcnt(0)
.Lmy_f_p2w:
	s_waitcnt vmcnt(1)
	v_lshlrev_b32_e32 v72, 16, v142
	v_and_b32_e32 v73, 0xffff0000, v142
	v_lshlrev_b32_e32 v76, 16, v144
	v_and_b32_e32 v77, 0xffff0000, v144
	v_lshlrev_b32_e32 v74, 16, v140
	v_and_b32_e32 v75, 0xffff0000, v140
	v_pk_add_f32 v[72:73], v[72:73], v[76:77]
	v_lshlrev_b32_e32 v78, 16, v156
	v_pk_fma_f32 v[72:73], v[72:73], 0.5, v[74:75] op_sel_hi:[1,0,1] neg_lo:[0,0,1] neg_hi:[0,0,1]
	v_and_b32_e32 v79, 0xffff0000, v156
	v_pk_fma_f32 v[72:73], v[0:1], v[72:73], v[74:75]
	v_lshlrev_b32_e32 v74, 16, v154
	v_and_b32_e32 v75, 0xffff0000, v154
	v_lshlrev_b32_e32 v76, 16, v152
	v_and_b32_e32 v77, 0xffff0000, v152
	v_pk_add_f32 v[74:75], v[74:75], v[78:79]
	v_cvt_f32_f16_e32 v21, v158
	v_pk_fma_f32 v[74:75], v[74:75], 0.5, v[76:77] op_sel_hi:[1,0,1] neg_lo:[0,0,1] neg_hi:[0,0,1]
	v_lshlrev_b32_e32 v80, 16, v145
	v_pk_fma_f32 v[76:77], v[8:9], v[74:75], v[76:77]
	v_lshlrev_b32_e32 v74, 16, v143
	v_and_b32_e32 v75, 0xffff0000, v143
	v_and_b32_e32 v81, 0xffff0000, v145
	v_lshlrev_b32_e32 v78, 16, v141
	v_and_b32_e32 v79, 0xffff0000, v141
	v_pk_add_f32 v[74:75], v[74:75], v[80:81]
	v_cvt_f32_f16_sdwa v84, v158 dst_sel:DWORD dst_unused:UNUSED_PAD src0_sel:WORD_1
	v_pk_fma_f32 v[74:75], v[74:75], 0.5, v[78:79] op_sel_hi:[1,0,1] neg_lo:[0,0,1] neg_hi:[0,0,1]
	v_lshlrev_b32_e32 v82, 16, v157
	v_pk_fma_f32 v[74:75], v[2:3], v[74:75], v[78:79]
	v_lshlrev_b32_e32 v78, 16, v155
	v_and_b32_e32 v79, 0xffff0000, v155
	v_and_b32_e32 v83, 0xffff0000, v157
	v_cvt_f32_f16_e32 v88, v159
	v_lshlrev_b32_e32 v80, 16, v153
	v_and_b32_e32 v81, 0xffff0000, v153
	v_pk_add_f32 v[78:79], v[78:79], v[82:83]
	v_mul_f32_e32 v21, 0xbf1b4598, v21
	v_pk_fma_f32 v[78:79], v[78:79], 0.5, v[80:81] op_sel_hi:[1,0,1] neg_lo:[0,0,1] neg_hi:[0,0,1]
	v_mul_f32_e32 v21, 0x3fb8aa3b, v21
	v_cvt_f32_f16_sdwa v89, v159 dst_sel:DWORD dst_unused:UNUSED_PAD src0_sel:WORD_1
	v_pk_fma_f32 v[78:79], v[10:11], v[78:79], v[80:81]
	v_exp_f32_e32 v80, v21
	v_mul_f32_e32 v21, 0xbf1b4598, v84
	v_mul_f32_e32 v21, 0x3fb8aa3b, v21
	v_lshlrev_b32_e32 v82, 16, v148
	v_and_b32_e32 v83, 0xffff0000, v148
	v_lshlrev_b32_e32 v86, 16, v150
	v_and_b32_e32 v87, 0xffff0000, v150
	v_exp_f32_e32 v81, v21
	v_lshlrev_b32_e32 v84, 16, v146
	v_and_b32_e32 v85, 0xffff0000, v146
	v_pk_add_f32 v[82:83], v[82:83], v[86:87]
	v_mul_f32_e32 v21, 0xbf1b4598, v88
	v_pk_fma_f32 v[82:83], v[82:83], 0.5, v[84:85] op_sel_hi:[1,0,1] neg_lo:[0,0,1] neg_hi:[0,0,1]
	v_mul_f32_e32 v21, 0x3fb8aa3b, v21
	v_pk_fma_f32 v[96:97], v[4:5], v[82:83], v[84:85]
	v_exp_f32_e32 v82, v21
	v_mul_f32_e32 v21, 0xbf1b4598, v89
	v_lshlrev_b32_e32 v84, 16, v149
	v_and_b32_e32 v85, 0xffff0000, v149
	v_lshlrev_b32_e32 v88, 16, v151
	v_and_b32_e32 v89, 0xffff0000, v151
	v_lshlrev_b32_e32 v86, 16, v147
	v_and_b32_e32 v87, 0xffff0000, v147
	v_pk_add_f32 v[84:85], v[84:85], v[88:89]
	v_cvt_f32_f16_sdwa v93, v160 dst_sel:DWORD dst_unused:UNUSED_PAD src0_sel:WORD_1
	v_pk_fma_f32 v[84:85], v[84:85], 0.5, v[86:87] op_sel_hi:[1,0,1] neg_lo:[0,0,1] neg_hi:[0,0,1]
	v_cvt_f32_f16_e32 v92, v160
	v_pk_fma_f32 v[94:95], v[6:7], v[84:85], v[86:87]
	v_pk_mul_f32 v[84:85], v[12:13], v[96:97]
	v_pk_mul_f32 v[88:89], v[14:15], v[94:95]
	v_pk_mul_f32 v[86:87], v[84:85], v[84:85]
	v_pk_mul_f32 v[90:91], v[88:89], v[88:89]
	v_add_f32_e32 v83, v86, v87
	v_add_f32_e32 v83, v90, v83
	v_add_f32_e32 v83, v91, v83
	v_cvt_f32_f16_sdwa v99, v161 dst_sel:DWORD dst_unused:UNUSED_PAD src0_sel:WORD_1
	v_cvt_f32_f16_e32 v98, v161
	v_add_f32_dpp v83, v83, v83 quad_perm:[1,0,3,2] row_mask:0xf bank_mask:0xf bound_ctrl:1
	v_mul_f32_e32 v21, 0x3fb8aa3b, v21
	s_bitcmp1_b32 s22, 0
	v_add_f32_dpp v83, v83, v83 quad_perm:[2,3,0,1] row_mask:0xf bank_mask:0xf bound_ctrl:1
	s_cselect_b32 s23, 0x2000, 0
	s_nop 0
	v_add_f32_dpp v83, v83, v83 row_half_mirror row_mask:0xf bank_mask:0xf bound_ctrl:1
	s_nop 1
	v_add_f32_dpp v83, v83, v83 row_mirror row_mask:0xf bank_mask:0xf bound_ctrl:1
	v_max_f32_e32 v83, 0x179abe15, v83
	v_rsq_f32_e32 v86, v83
	v_exp_f32_e32 v83, v21
	v_add_u32_e32 v21, s23, v67
	v_pk_mul_f32 v[90:91], v[84:85], v[86:87] op_sel_hi:[1,0]
	v_pk_mul_f32 v[100:101], v[88:89], v[86:87] op_sel_hi:[1,0]
	v_xor_b32_e32 v85, 0x80000000, v91
	v_xor_b32_e32 v84, 0x80000000, v90
	v_pk_mul_f32 v[88:89], v[90:91], v[92:93]
	v_pk_mul_f32 v[90:91], v[100:101], v[98:99]
	v_pk_add_f32 v[92:93], v[92:93], -1.0 op_sel_hi:[1,0]
	v_pk_add_f32 v[98:99], v[98:99], -1.0 op_sel_hi:[1,0]
	v_pk_fma_f32 v[92:93], v[16:17], v[92:93], 1.0 op_sel_hi:[1,1,0]
	v_pk_fma_f32 v[98:99], v[18:19], v[98:99], 1.0 op_sel_hi:[1,1,0]
	v_xor_b32_e32 v86, 0x80000000, v100
	v_xor_b32_e32 v87, 0x80000000, v101
	v_pk_mul_f32 v[94:95], v[94:95], v[98:99]
	v_pk_mul_f32 v[92:93], v[96:97], v[92:93]
	ds_write_b128 v67, v[80:83]
	ds_write_b128 v67, v[84:87] offset:8192
	ds_write_b128 v67, v[88:91] offset:16384
	ds_write_b128 v67, v[92:95] offset:24576
	ds_write_b128 v67, v[72:75] offset:32768
	ds_write_b128 v21, v[76:79] offset:40960
	s_lshl_b32 s96, s100, 8
	v_subrev_u32_e32 v67, s96, v67
	s_cmp_gt_u32 s65, 61
	s_cbranch_scc1 .Lmy_f_nol34
	s_cmp_eq_u32 s65, 61
	s_cbranch_scc1 .Lmy_f_slow34
	s_cmp_lg_u32 s4, 0
	s_mov_b32 s100, 0xfffd0000
	s_cselect_b32 s100, 0x30000, s100
	s_cselect_b32 s101, 0, -1
	s_mov_b32 s96, 0xfffc0000
	s_cselect_b32 s96, 0x40000, s96
	s_cselect_b32 s97, 0, -1
	v_lshl_add_u64 v[166:167], v[166:167], 0, s[100:101]
	v_lshl_add_u64 v[164:165], v[164:165], 0, s[100:101]
	v_lshl_add_u64 v[168:169], v[168:169], 0, s[100:101]
	v_lshl_add_u64 v[170:171], v[170:171], 0, s[96:97]
	global_load_dwordx2 v[26:27], v[166:167], off
	global_load_dwordx2 v[28:29], v[164:165], off offset:2048
	global_load_dwordx2 v[30:31], v[168:169], off offset:-2048
	global_load_dwordx2 v[32:33], v[166:167], off offset:2048
	global_load_dwordx2 v[34:35], v[166:167], off offset:-4096
	global_load_dwordx2 v[36:37], v[168:169], off
	global_load_dwordx2 v[38:39], v[168:169], off offset:-4096
	global_load_dwordx2 v[40:41], v[166:167], off offset:-2048
	global_load_dwordx2 v[42:43], v[168:169], off offset:2048
	global_load_dwordx2 v[44:45], v[170:171], off offset:-2048
	global_load_dwordx2 v[46:47], v[170:171], off offset:2048
	v_lshl_add_u64 v[174:175], v[174:175], 0, s[100:101]
	v_lshl_add_u64 v[172:173], v[172:173], 0, s[100:101]
	v_lshl_add_u64 v[176:177], v[176:177], 0, s[100:101]
	v_lshl_add_u64 v[178:179], v[178:179], 0, s[96:97]
	global_load_dwordx2 v[140:141], v[174:175], off
	global_load_dwordx2 v[142:143], v[172:173], off offset:2048
	global_load_dwordx2 v[144:145], v[176:177], off offset:-2048
	global_load_dwordx2 v[146:147], v[174:175], off offset:2048
	global_load_dwordx2 v[148:149], v[174:175], off offset:-4096
	global_load_dwordx2 v[150:151], v[176:177], off
	global_load_dwordx2 v[152:153], v[176:177], off offset:-4096
	global_load_dwordx2 v[154:155], v[174:175], off offset:-2048
	global_load_dwordx2 v[156:157], v[176:177], off offset:2048
	global_load_dwordx2 v[158:159], v[178:179], off offset:-2048
	global_load_dwordx2 v[160:161], v[178:179], off offset:2048
	s_branch .Lmy_f_nol34
